# first grid barrier census: 16 counter loads issued together; diff epilogue gain loads batched
# speedup vs baseline: 1.0076x; 1.0018x over previous
; __device__ __forceinline__ unsigned xb_ld(unsigned* p)              { return __hip_atomic_load(p, __ATOMIC_RELAXED, __HIP_MEMORY_SCOPE_AGENT); }
; __device__ __forceinline__ void xcd_barrier_complete(unsigned* bar, unsigned x, unsigned& nloc, unsigned& nx) {
;     const unsigned G = gridDim.x * gridDim.y * gridDim.z;
;     unsigned sum, cnt, mine, sp = 0u;
;     for (;;) {
;         sum = 0u; cnt = 0u; mine = 0u;
; #pragma unroll
;         for (unsigned j = 0; j < 16; ++j) { const unsigned c = xb_ld(&bar[XB_XCNT(j)]); sum += c; cnt += (c > 0u) ? 1u : 0u; mine = (j == x) ? c : mine; }
;         if (sum == G) break;
;         __builtin_amdgcn_s_sleep(1);
;         if ((++sp & 255u) == 0u) { if (xb_ld(&bar[XB_TMO])) break; if (sp > XB_SPIN_CAP) { atomicAdd(&bar[XB_TMO], 1u); break; } }
;     }
.LBB0_707:
	v_readlane_b32 s4, v252, 44
	v_readlane_b32 s5, v252, 45
	v_readlane_b32 s10, v254, 23
	s_waitcnt lgkmcnt(0)
	s_nop 4
	global_load_dword v0, v197, s[4:5] sc1
	global_load_dword v1, v197, s[4:5] offset:256 sc1
	global_load_dword v2, v197, s[4:5] offset:512 sc1
	global_load_dword v3, v197, s[4:5] offset:768 sc1
	global_load_dword v4, v197, s[4:5] offset:1024 sc1
	global_load_dword v5, v197, s[4:5] offset:1280 sc1
	global_load_dword v6, v197, s[4:5] offset:1536 sc1
	global_load_dword v7, v197, s[4:5] offset:1792 sc1
	global_load_dword v8, v197, s[4:5] offset:2048 sc1
	global_load_dword v9, v197, s[4:5] offset:2304 sc1
	global_load_dword v10, v197, s[4:5] offset:2560 sc1
	global_load_dword v11, v197, s[4:5] offset:2816 sc1
	global_load_dword v12, v197, s[4:5] offset:3072 sc1
	global_load_dword v13, v197, s[4:5] offset:3328 sc1
	global_load_dword v14, v197, s[4:5] offset:3584 sc1
	global_load_dword v15, v197, s[4:5] offset:3840 sc1
	s_mov_b64 s[4:5], -1
	s_waitcnt vmcnt(0)
	v_add_u32_e32 v16, v1, v0
	v_add_u32_e32 v16, v16, v2
	v_add_u32_e32 v16, v16, v3
	v_add_u32_e32 v16, v16, v4
	v_add_u32_e32 v16, v16, v5
	v_add_u32_e32 v16, v16, v6
	v_add_u32_e32 v16, v16, v7
	v_add_u32_e32 v16, v16, v8
	v_add_u32_e32 v16, v16, v9
	v_add_u32_e32 v16, v16, v10
	v_add_u32_e32 v16, v16, v11
	v_add_u32_e32 v16, v16, v12
	v_add_u32_e32 v16, v16, v13
	v_add_u32_e32 v16, v16, v14
	v_add_u32_e32 v16, v16, v15
	v_cmp_eq_u32_e32 vcc, s10, v16
	s_mov_b64 s[10:11], -1
	s_cbranch_vccnz .LBB0_706
	s_and_b32 s4, s14, 0xff
	s_cmp_eq_u32 s4, 0
	s_mov_b64 s[4:5], -1
	s_mov_b64 s[12:13], -1
	s_sleep 1
	s_cbranch_scc0 .LBB0_711
	v_readlane_b32 s4, v252, 42
	v_readlane_b32 s5, v252, 43
	s_nop 4
	global_load_dword v16, v197, s[4:5] sc1
	s_waitcnt vmcnt(0)
	v_cmp_eq_u32_e32 vcc, 0, v16
	s_cbranch_vccnz .LBB0_713
	s_mov_b64 s[12:13], 0
	s_mov_b64 s[4:5], -1
